# v17 + early-WG pass-B arrival also moved to decode wave 7; SSD-state poll/invalidate by thread 0 only followed by a WG barrier (1 L2 invalidate per WG instead of 8)
# speedup vs baseline: 1.0347x; 1.0099x over previous
; #define LAS __attribute__((address_space(3)))
; #define STAMP() do { if (PROBE_SEG >= 0 && bx == 0 && tid == 0) { tst[nst] = __builtin_amdgcn_s_memrealtime(); } ++nst; } while (0)
; #define BOTH(k) (IN(k) && IN((k) + 1))
; __global__ void __launch_bounds__(512, 2) hymba_fwd(Params p) {
;     ...
;         {
;             const int nfull = (MROWS / 256) * (NPAD / 256) + (MMEM / 256) * (1024 / 256) - ((MROWS / 256) * (NPAD / 256) + (MMEM / 256) * (1024 / 256)) / G * G;
;             const int first_idle = (nfull == 0) ? 0 : nfull, nidle = G - first_idle;
;             if (bx >= first_idle) {
;                 const int lane = tid & 63, wave = __builtin_amdgcn_readfirstlane(tid >> 6);
;                 tr_pipeline(p, (LAS float*)(lds + wave * 16896), lane, (bx - first_idle) * 8 + wave, nidle * 8, NITEMS_P0, NITEMS_ALL);
;                 cache_mem_convert(p, (bx - first_idle) * 512 + tid, nidle * 512);
;             }
;         }
;         if (BOTH(1)) GBAR(); STAMP();
;     }
;     if (IN(3)) { phase3<31>(p, lds, ctlw, 0); if (BOTH(3)) GBAR(); STAMP(); }
.LBB0_576:
	s_cmp_eq_u32 s98, 1
	s_cbranch_scc0 .Lp1_bar
	s_mov_b32 s98, 2
	s_waitcnt vmcnt(0) lgkmcnt(0)
	s_barrier
	v_readlane_b32 s6, v254, 3
	v_readlane_b32 s7, v254, 4
	s_branch .LBB0_626

; #define LAS __attribute__((address_space(3)))
; template <int MASK> __device__ __forceinline__ void phase3(const Params& p, LAS unsigned char* lds, volatile LAS unsigned* ctlw, int qset) {
;     ...
;         LAS unsigned char* wlds = lds + (wid < 4 ? wid * 19456 : 77824 + (wid - 4) * 19456);
;         decode_wave_loop((const int*)p.in[I_PT], p.in[I_CK], p.in[I_CV], p.in[I_SBBIAS], p.ws, wlds, qbase + 64 * 1, lane);
.LBB0_961:
	s_cmp_lg_u32 s24, 7
	s_cbranch_scc1 .Llz_skip
	s_and_saveexec_b64 s[10:11], s[2:3]
	v_mov_b32_e32 v2, 0xa00
	v_mov_b32_e32 v3, 1
	v_readlane_b32 s12, v254, 9
	s_cmpk_gt_i32 s12, 0x93
	s_cbranch_scc1 .Llz_early
	buffer_wbl2 sc1
	s_waitcnt vmcnt(0)
	global_atomic_add v2, v3, s[90:91]
.Llz_early:
	global_atomic_add v2, v3, s[90:91] offset:-512
	s_waitcnt vmcnt(0)
	s_or_b64 exec, exec, s[10:11]

; #define STAMP() do { if (PROBE_SEG >= 0 && bx == 0 && tid == 0) { tst[nst] = __builtin_amdgcn_s_memrealtime(); } ++nst; } while (0)
; #define BOTH(k) (IN(k) && IN((k) + 1))
; __global__ void __launch_bounds__(512, 2) hymba_fwd(Params p) {
;     ...
;     if (IN(3)) { phase3<31>(p, lds, ctlw, 0); if (BOTH(3)) GBAR(); STAMP(); }
;     if (IN(4)) { phase4(p, lds, ctlw, vcu, G, 0); if (BOTH(4)) GBAR(); STAMP(); }
.LBB0_1001:
	v_readlane_b32 s6, v254, 3
	v_readlane_b32 s7, v254, 4
	s_cmp_lt_i32 s7, 5
	s_waitcnt lgkmcnt(0)
	s_barrier
	s_cbranch_scc1 .LBB0_1051
	s_cmp_lg_u32 s98, 2
	s_cbranch_scc1 .Lp3_bar3
	s_mov_b32 s98, 3
	s_and_saveexec_b64 s[2:3], s[0:1]
	s_cbranch_execz .Lst_poll_end
	s_mov_b32 s5, 0x8000
	v_mov_b32_e32 v2, 0

; #define STAMP() do { if (PROBE_SEG >= 0 && bx == 0 && tid == 0) { tst[nst] = __builtin_amdgcn_s_memrealtime(); } ++nst; } while (0)
; #define BOTH(k) (IN(k) && IN((k) + 1))
; __global__ void __launch_bounds__(512, 2) hymba_fwd(Params p) {
;     ...
;     if (IN(3)) { phase3<31>(p, lds, ctlw, 0); if (BOTH(3)) GBAR(); STAMP(); }
;     if (IN(4)) { phase4(p, lds, ctlw, vcu, G, 0); if (BOTH(4)) GBAR(); STAMP(); }
.Lst_poll_end:
	s_or_b64 exec, exec, s[2:3]
	s_barrier
	s_branch .LBB0_1074
